# prepass modulation GEMV: pairs of loop iterations merged so 16 row loads are in flight before the first multiply (4 serial memory round trips -> 2)
# baseline (speedup 1.0000x reference)
.LBB0_54:
	v_lshl_add_u64 v[46:47], v[44:45], 0, s[8:9]
	s_movk_i32 s7, 0x6000
	v_add_co_u32_e32 v68, vcc, s7, v46
	s_mov_b32 s7, 0xc000
	s_nop 0
	v_addc_co_u32_e32 v69, vcc, 0, v47, vcc
	v_add_co_u32_e32 v72, vcc, s7, v46
	s_mov_b32 s7, 0x12000
	s_nop 0
	v_addc_co_u32_e32 v73, vcc, 0, v47, vcc
	v_add_co_u32_e32 v76, vcc, s7, v46
	s_mov_b32 s7, 0x18000
	s_nop 0
	v_addc_co_u32_e32 v77, vcc, 0, v47, vcc
	global_load_dwordx4 v[64:67], v[46:47], off nt
	v_add_co_u32_e32 v80, vcc, s7, v46
	s_mov_b32 s7, 0x1e000
	s_nop 0
	v_addc_co_u32_e32 v81, vcc, 0, v47, vcc
	v_add_co_u32_e32 v84, vcc, s7, v46
	s_mov_b32 s7, 0x24000
	s_nop 0
	v_addc_co_u32_e32 v85, vcc, 0, v47, vcc
	v_add_co_u32_e32 v88, vcc, s7, v46
	s_mov_b32 s7, 0x2a000
	s_nop 0
	v_addc_co_u32_e32 v89, vcc, 0, v47, vcc
	v_add_co_u32_e32 v46, vcc, s7, v46
	s_add_u32 s8, s8, 0x30000
	s_addc_u32 s9, s9, 0
	s_nop 0
	v_addc_co_u32_e32 v47, vcc, 0, v47, vcc
	global_load_dwordx4 v[68:71], v[68:69], off nt
	s_nop 0
	global_load_dwordx4 v[72:75], v[72:73], off nt
	s_nop 0
	global_load_dwordx4 v[76:79], v[76:77], off nt
	s_nop 0
	global_load_dwordx4 v[80:83], v[80:81], off nt
	s_nop 0
	global_load_dwordx4 v[84:87], v[84:85], off nt
	s_nop 0
	global_load_dwordx4 v[88:91], v[88:89], off nt
	s_nop 0
	global_load_dwordx4 v[92:95], v[46:47], off nt
	v_lshl_add_u64 v[202:203], v[44:45], 0, s[8:9]
	s_movk_i32 s7, 0x6000
	v_add_co_u32_e32 v174, vcc, s7, v202
	s_mov_b32 s7, 0xc000
	s_nop 0
	v_addc_co_u32_e32 v175, vcc, 0, v203, vcc
	v_add_co_u32_e32 v178, vcc, s7, v202
	s_mov_b32 s7, 0x12000
	s_nop 0
	v_addc_co_u32_e32 v179, vcc, 0, v203, vcc
	v_add_co_u32_e32 v182, vcc, s7, v202
	s_mov_b32 s7, 0x18000
	s_nop 0
	v_addc_co_u32_e32 v183, vcc, 0, v203, vcc
	global_load_dwordx4 v[170:173], v[202:203], off nt
	v_add_co_u32_e32 v186, vcc, s7, v202
	s_mov_b32 s7, 0x1e000
	s_nop 0
	v_addc_co_u32_e32 v187, vcc, 0, v203, vcc
	v_add_co_u32_e32 v190, vcc, s7, v202
	s_mov_b32 s7, 0x24000
	s_nop 0
	v_addc_co_u32_e32 v191, vcc, 0, v203, vcc
	v_add_co_u32_e32 v194, vcc, s7, v202
	s_mov_b32 s7, 0x2a000
	s_nop 0
	v_addc_co_u32_e32 v195, vcc, 0, v203, vcc
	v_add_co_u32_e32 v202, vcc, s7, v202
	s_add_u32 s8, s8, 0x30000
	s_addc_u32 s9, s9, 0
	s_nop 0
	v_addc_co_u32_e32 v203, vcc, 0, v203, vcc
	global_load_dwordx4 v[174:177], v[174:175], off nt
	s_nop 0
	global_load_dwordx4 v[178:181], v[178:179], off nt
	s_nop 0
	global_load_dwordx4 v[182:185], v[182:183], off nt
	s_nop 0
	global_load_dwordx4 v[186:189], v[186:187], off nt
	s_nop 0
	global_load_dwordx4 v[190:193], v[190:191], off nt
	s_nop 0
	global_load_dwordx4 v[194:197], v[194:195], off nt
	s_nop 0
	global_load_dwordx4 v[198:201], v[202:203], off nt
	ds_read_b128 v[96:99], v12
	ds_read_b128 v[100:103], v12 offset:16
	ds_read_b128 v[104:107], v12 offset:4096
	ds_read_b128 v[108:111], v12 offset:4112
	ds_read_b128 v[112:115], v12 offset:8192
	ds_read_b128 v[116:119], v12 offset:8208
	s_waitcnt lgkmcnt(5)
	v_mov_b32_e32 v46, v99
	s_waitcnt lgkmcnt(3)
	v_mov_b32_e32 v120, v107
	s_waitcnt lgkmcnt(1)
	v_mov_b32_e32 v122, v115
	v_mov_b32_e32 v124, v103
	v_mov_b32_e32 v126, v111
	s_waitcnt lgkmcnt(0)
	v_mov_b32_e32 v128, v119
	v_add_u32_e32 v12, 32, v12
	s_cmp_eq_u32 s8, 0xc0000
	s_waitcnt vmcnt(15)
	v_pk_fma_f32 v[2:3], v[66:67], v[96:97], v[2:3] op_sel_hi:[1,0,1]
	v_pk_fma_f32 v[0:1], v[64:65], v[96:97], v[0:1] op_sel_hi:[1,0,1]
	v_pk_fma_f32 v[6:7], v[66:67], v[104:105], v[6:7] op_sel_hi:[1,0,1]
	v_pk_fma_f32 v[4:5], v[64:65], v[104:105], v[4:5] op_sel_hi:[1,0,1]
	v_pk_fma_f32 v[10:11], v[66:67], v[112:113], v[10:11] op_sel_hi:[1,0,1]
	v_pk_fma_f32 v[8:9], v[64:65], v[112:113], v[8:9] op_sel_hi:[1,0,1]
	s_waitcnt vmcnt(14)
	v_pk_fma_f32 v[0:1], v[68:69], v[96:97], v[0:1] op_sel:[0,1,0]
	v_pk_fma_f32 v[2:3], v[70:71], v[96:97], v[2:3] op_sel:[0,1,0]
	v_pk_fma_f32 v[4:5], v[68:69], v[104:105], v[4:5] op_sel:[0,1,0]
	v_pk_fma_f32 v[6:7], v[70:71], v[104:105], v[6:7] op_sel:[0,1,0]
	v_pk_fma_f32 v[8:9], v[68:69], v[112:113], v[8:9] op_sel:[0,1,0]
	v_pk_fma_f32 v[10:11], v[70:71], v[112:113], v[10:11] op_sel:[0,1,0]
	s_waitcnt vmcnt(13)
	v_pk_fma_f32 v[2:3], v[74:75], v[98:99], v[2:3] op_sel_hi:[1,0,1]
	v_pk_fma_f32 v[0:1], v[72:73], v[98:99], v[0:1] op_sel_hi:[1,0,1]
	v_pk_fma_f32 v[6:7], v[74:75], v[106:107], v[6:7] op_sel_hi:[1,0,1]
	v_pk_fma_f32 v[4:5], v[72:73], v[106:107], v[4:5] op_sel_hi:[1,0,1]
	v_pk_fma_f32 v[10:11], v[74:75], v[114:115], v[10:11] op_sel_hi:[1,0,1]
	v_pk_fma_f32 v[8:9], v[72:73], v[114:115], v[8:9] op_sel_hi:[1,0,1]
	s_waitcnt vmcnt(12)
	v_pk_fma_f32 v[2:3], v[78:79], v[46:47], v[2:3] op_sel_hi:[1,0,1]
	v_pk_fma_f32 v[0:1], v[76:77], v[46:47], v[0:1] op_sel_hi:[1,0,1]
	v_pk_fma_f32 v[6:7], v[78:79], v[120:121], v[6:7] op_sel_hi:[1,0,1]
	v_pk_fma_f32 v[4:5], v[76:77], v[120:121], v[4:5] op_sel_hi:[1,0,1]
	v_pk_fma_f32 v[10:11], v[78:79], v[122:123], v[10:11] op_sel_hi:[1,0,1]
	v_pk_fma_f32 v[8:9], v[76:77], v[122:123], v[8:9] op_sel_hi:[1,0,1]
	s_waitcnt vmcnt(11)
	v_pk_fma_f32 v[2:3], v[82:83], v[100:101], v[2:3] op_sel_hi:[1,0,1]
	v_pk_fma_f32 v[0:1], v[80:81], v[100:101], v[0:1] op_sel_hi:[1,0,1]
	v_pk_fma_f32 v[6:7], v[82:83], v[108:109], v[6:7] op_sel_hi:[1,0,1]
	v_pk_fma_f32 v[4:5], v[80:81], v[108:109], v[4:5] op_sel_hi:[1,0,1]
	v_pk_fma_f32 v[10:11], v[82:83], v[116:117], v[10:11] op_sel_hi:[1,0,1]
	v_pk_fma_f32 v[8:9], v[80:81], v[116:117], v[8:9] op_sel_hi:[1,0,1]
	s_waitcnt vmcnt(10)
	v_pk_fma_f32 v[2:3], v[86:87], v[100:101], v[2:3] op_sel:[0,1,0]
	v_pk_fma_f32 v[0:1], v[84:85], v[100:101], v[0:1] op_sel:[0,1,0]
	v_pk_fma_f32 v[6:7], v[86:87], v[108:109], v[6:7] op_sel:[0,1,0]
	v_pk_fma_f32 v[4:5], v[84:85], v[108:109], v[4:5] op_sel:[0,1,0]
	v_pk_fma_f32 v[10:11], v[86:87], v[116:117], v[10:11] op_sel:[0,1,0]
	v_pk_fma_f32 v[8:9], v[84:85], v[116:117], v[8:9] op_sel:[0,1,0]
	s_waitcnt vmcnt(9)
	v_pk_fma_f32 v[2:3], v[90:91], v[102:103], v[2:3] op_sel_hi:[1,0,1]
	v_pk_fma_f32 v[0:1], v[88:89], v[102:103], v[0:1] op_sel_hi:[1,0,1]
	v_pk_fma_f32 v[6:7], v[90:91], v[110:111], v[6:7] op_sel_hi:[1,0,1]
	v_pk_fma_f32 v[4:5], v[88:89], v[110:111], v[4:5] op_sel_hi:[1,0,1]
	v_pk_fma_f32 v[10:11], v[90:91], v[118:119], v[10:11] op_sel_hi:[1,0,1]
	v_pk_fma_f32 v[8:9], v[88:89], v[118:119], v[8:9] op_sel_hi:[1,0,1]
	s_waitcnt vmcnt(8)
	v_pk_fma_f32 v[2:3], v[94:95], v[124:125], v[2:3] op_sel_hi:[1,0,1]
	v_pk_fma_f32 v[0:1], v[92:93], v[124:125], v[0:1] op_sel_hi:[1,0,1]
	v_pk_fma_f32 v[6:7], v[94:95], v[126:127], v[6:7] op_sel_hi:[1,0,1]
	v_pk_fma_f32 v[4:5], v[92:93], v[126:127], v[4:5] op_sel_hi:[1,0,1]
	v_pk_fma_f32 v[10:11], v[94:95], v[128:129], v[10:11] op_sel_hi:[1,0,1]
	v_pk_fma_f32 v[8:9], v[92:93], v[128:129], v[8:9] op_sel_hi:[1,0,1]
	ds_read_b128 v[96:99], v12
	ds_read_b128 v[100:103], v12 offset:16
	ds_read_b128 v[104:107], v12 offset:4096
	ds_read_b128 v[108:111], v12 offset:4112
	ds_read_b128 v[112:115], v12 offset:8192
	ds_read_b128 v[116:119], v12 offset:8208
	s_waitcnt lgkmcnt(5)
	v_mov_b32_e32 v46, v99
	s_waitcnt lgkmcnt(3)
	v_mov_b32_e32 v120, v107
	s_waitcnt lgkmcnt(1)
	v_mov_b32_e32 v122, v115
	v_mov_b32_e32 v124, v103
	v_mov_b32_e32 v126, v111
	s_waitcnt lgkmcnt(0)
	v_mov_b32_e32 v128, v119
	v_add_u32_e32 v12, 32, v12
	s_cmp_eq_u32 s8, 0xc0000
	s_waitcnt vmcnt(7)
	v_pk_fma_f32 v[2:3], v[172:173], v[96:97], v[2:3] op_sel_hi:[1,0,1]
	v_pk_fma_f32 v[0:1], v[170:171], v[96:97], v[0:1] op_sel_hi:[1,0,1]
	v_pk_fma_f32 v[6:7], v[172:173], v[104:105], v[6:7] op_sel_hi:[1,0,1]
	v_pk_fma_f32 v[4:5], v[170:171], v[104:105], v[4:5] op_sel_hi:[1,0,1]
	v_pk_fma_f32 v[10:11], v[172:173], v[112:113], v[10:11] op_sel_hi:[1,0,1]
	v_pk_fma_f32 v[8:9], v[170:171], v[112:113], v[8:9] op_sel_hi:[1,0,1]
	s_waitcnt vmcnt(6)
	v_pk_fma_f32 v[0:1], v[174:175], v[96:97], v[0:1] op_sel:[0,1,0]
	v_pk_fma_f32 v[2:3], v[176:177], v[96:97], v[2:3] op_sel:[0,1,0]
	v_pk_fma_f32 v[4:5], v[174:175], v[104:105], v[4:5] op_sel:[0,1,0]
	v_pk_fma_f32 v[6:7], v[176:177], v[104:105], v[6:7] op_sel:[0,1,0]
	v_pk_fma_f32 v[8:9], v[174:175], v[112:113], v[8:9] op_sel:[0,1,0]
	v_pk_fma_f32 v[10:11], v[176:177], v[112:113], v[10:11] op_sel:[0,1,0]
	s_waitcnt vmcnt(5)
	v_pk_fma_f32 v[2:3], v[180:181], v[98:99], v[2:3] op_sel_hi:[1,0,1]
	v_pk_fma_f32 v[0:1], v[178:179], v[98:99], v[0:1] op_sel_hi:[1,0,1]
	v_pk_fma_f32 v[6:7], v[180:181], v[106:107], v[6:7] op_sel_hi:[1,0,1]
	v_pk_fma_f32 v[4:5], v[178:179], v[106:107], v[4:5] op_sel_hi:[1,0,1]
	v_pk_fma_f32 v[10:11], v[180:181], v[114:115], v[10:11] op_sel_hi:[1,0,1]
	v_pk_fma_f32 v[8:9], v[178:179], v[114:115], v[8:9] op_sel_hi:[1,0,1]
	s_waitcnt vmcnt(4)
	v_pk_fma_f32 v[2:3], v[184:185], v[46:47], v[2:3] op_sel_hi:[1,0,1]
	v_pk_fma_f32 v[0:1], v[182:183], v[46:47], v[0:1] op_sel_hi:[1,0,1]
	v_pk_fma_f32 v[6:7], v[184:185], v[120:121], v[6:7] op_sel_hi:[1,0,1]
	v_pk_fma_f32 v[4:5], v[182:183], v[120:121], v[4:5] op_sel_hi:[1,0,1]
	v_pk_fma_f32 v[10:11], v[184:185], v[122:123], v[10:11] op_sel_hi:[1,0,1]
	v_pk_fma_f32 v[8:9], v[182:183], v[122:123], v[8:9] op_sel_hi:[1,0,1]
	s_waitcnt vmcnt(3)
	v_pk_fma_f32 v[2:3], v[188:189], v[100:101], v[2:3] op_sel_hi:[1,0,1]
	v_pk_fma_f32 v[0:1], v[186:187], v[100:101], v[0:1] op_sel_hi:[1,0,1]
	v_pk_fma_f32 v[6:7], v[188:189], v[108:109], v[6:7] op_sel_hi:[1,0,1]
	v_pk_fma_f32 v[4:5], v[186:187], v[108:109], v[4:5] op_sel_hi:[1,0,1]
	v_pk_fma_f32 v[10:11], v[188:189], v[116:117], v[10:11] op_sel_hi:[1,0,1]
	v_pk_fma_f32 v[8:9], v[186:187], v[116:117], v[8:9] op_sel_hi:[1,0,1]
	s_waitcnt vmcnt(2)
	v_pk_fma_f32 v[2:3], v[192:193], v[100:101], v[2:3] op_sel:[0,1,0]
	v_pk_fma_f32 v[0:1], v[190:191], v[100:101], v[0:1] op_sel:[0,1,0]
	v_pk_fma_f32 v[6:7], v[192:193], v[108:109], v[6:7] op_sel:[0,1,0]
	v_pk_fma_f32 v[4:5], v[190:191], v[108:109], v[4:5] op_sel:[0,1,0]
	v_pk_fma_f32 v[10:11], v[192:193], v[116:117], v[10:11] op_sel:[0,1,0]
	v_pk_fma_f32 v[8:9], v[190:191], v[116:117], v[8:9] op_sel:[0,1,0]
	s_waitcnt vmcnt(1)
	v_pk_fma_f32 v[2:3], v[196:197], v[102:103], v[2:3] op_sel_hi:[1,0,1]
	v_pk_fma_f32 v[0:1], v[194:195], v[102:103], v[0:1] op_sel_hi:[1,0,1]
	v_pk_fma_f32 v[6:7], v[196:197], v[110:111], v[6:7] op_sel_hi:[1,0,1]
	v_pk_fma_f32 v[4:5], v[194:195], v[110:111], v[4:5] op_sel_hi:[1,0,1]
	v_pk_fma_f32 v[10:11], v[196:197], v[118:119], v[10:11] op_sel_hi:[1,0,1]
	v_pk_fma_f32 v[8:9], v[194:195], v[118:119], v[8:9] op_sel_hi:[1,0,1]
	s_waitcnt vmcnt(0)
	v_pk_fma_f32 v[2:3], v[200:201], v[124:125], v[2:3] op_sel_hi:[1,0,1]
	v_pk_fma_f32 v[0:1], v[198:199], v[124:125], v[0:1] op_sel_hi:[1,0,1]
	v_pk_fma_f32 v[6:7], v[200:201], v[126:127], v[6:7] op_sel_hi:[1,0,1]
	v_pk_fma_f32 v[4:5], v[198:199], v[126:127], v[4:5] op_sel_hi:[1,0,1]
	v_pk_fma_f32 v[10:11], v[200:201], v[128:129], v[10:11] op_sel_hi:[1,0,1]
	v_pk_fma_f32 v[8:9], v[198:199], v[128:129], v[8:9] op_sel_hi:[1,0,1]
	s_cbranch_scc0 .LBB0_54
	ds_write_b128 v56, v[0:3] offset:12288
	ds_write_b128 v56, v[4:7] offset:12544
	ds_write_b128 v56, v[8:11] offset:12800
	s_waitcnt lgkmcnt(0)
	s_barrier
	s_and_saveexec_b64 s[8:9], s[4:5]
	s_cbranch_execz .LBB0_22
	s_mul_i32 s7, s3, 0x1800
	s_add_i32 s7, s7, s6
	v_or_b32_e32 v0, s7, v149
	v_readlane_b32 s12, v219, 9
	v_ashrrev_i32_e32 v1, 31, v0
	v_readlane_b32 s14, v219, 11
	v_readlane_b32 s15, v219, 12
	v_readlane_b32 s13, v219, 10
	v_readlane_b32 s16, v219, 13
	v_lshl_add_u64 v[0:1], v[0:1], 2, s[14:15]
	global_load_dword v12, v[0:1], off
	ds_read2st64_b32 v[0:1], v58 offset0:48 offset1:51
	ds_read2st64_b32 v[2:3], v58 offset0:54 offset1:57
	ds_read2st64_b32 v[4:5], v58 offset0:60 offset1:63
	ds_read2st64_b32 v[6:7], v58 offset0:66 offset1:69
	ds_read2st64_b32 v[8:9], v58 offset0:72 offset1:75
	ds_read2st64_b32 v[10:11], v58 offset0:78 offset1:81
	ds_read2st64_b32 v[44:45], v58 offset0:84 offset1:87
	ds_read2st64_b32 v[46:47], v58 offset0:90 offset1:93
	ds_read2st64_b32 v[64:65], v58 offset0:96 offset1:99
	ds_read2st64_b32 v[66:67], v58 offset0:102 offset1:105
	ds_read2st64_b32 v[68:69], v58 offset0:108 offset1:111
	ds_read2st64_b32 v[70:71], v58 offset0:114 offset1:117
	ds_read2st64_b32 v[72:73], v58 offset0:120 offset1:123
	ds_read2st64_b32 v[74:75], v58 offset0:126 offset1:129
	ds_read2st64_b32 v[76:77], v58 offset0:132 offset1:135
	ds_read2st64_b32 v[78:79], v58 offset0:138 offset1:141
	v_mad_u64_u32 v[80:81], s[14:15], s3, 3, v[148:149]
	s_movk_i32 s3, 0x1800
	v_mul_lo_u32 v25, v80, s3
	v_add_u32_e32 v25, s6, v25
	v_or_b32_e32 v80, v25, v149
	v_ashrrev_i32_e32 v81, 31, v80
	v_readlane_b32 s17, v219, 14
	v_readlane_b32 s18, v219, 15
	v_readlane_b32 s19, v219, 16
	v_readlane_b32 s20, v219, 17
	v_readlane_b32 s21, v219, 18
	v_readlane_b32 s22, v219, 19
	v_readlane_b32 s23, v219, 20
	v_readlane_b32 s24, v219, 21
	v_readlane_b32 s25, v219, 22
	v_readlane_b32 s26, v219, 23
	v_readlane_b32 s27, v219, 24
	s_waitcnt vmcnt(0) lgkmcnt(14)
	v_add_f32_e32 v0, v12, v0
	v_add_f32_e32 v0, v0, v1
	v_add_f32_e32 v0, v0, v2
	v_add_f32_e32 v0, v0, v3
	s_waitcnt lgkmcnt(13)
	v_add_f32_e32 v0, v0, v4
	v_add_f32_e32 v0, v0, v5
	s_waitcnt lgkmcnt(12)
	v_add_f32_e32 v0, v0, v6
	v_add_f32_e32 v0, v0, v7
	s_waitcnt lgkmcnt(11)
	v_add_f32_e32 v0, v0, v8
	v_add_f32_e32 v0, v0, v9
	s_waitcnt lgkmcnt(10)
	v_add_f32_e32 v0, v0, v10
	v_add_f32_e32 v0, v0, v11
	s_waitcnt lgkmcnt(9)
	v_add_f32_e32 v0, v0, v44
	v_add_f32_e32 v0, v0, v45
	s_waitcnt lgkmcnt(8)
	v_add_f32_e32 v0, v0, v46
	v_add_f32_e32 v0, v0, v47
	s_waitcnt lgkmcnt(7)
	v_add_f32_e32 v0, v0, v64
	v_add_f32_e32 v0, v0, v65
	s_waitcnt lgkmcnt(6)
	v_add_f32_e32 v0, v0, v66
	v_add_f32_e32 v0, v0, v67
	s_waitcnt lgkmcnt(5)
	v_add_f32_e32 v0, v0, v68
	v_add_f32_e32 v0, v0, v69
	s_waitcnt lgkmcnt(4)
	v_add_f32_e32 v0, v0, v70
	v_add_f32_e32 v0, v0, v71
	s_waitcnt lgkmcnt(3)
	v_add_f32_e32 v0, v0, v72
	v_add_f32_e32 v0, v0, v73
	s_waitcnt lgkmcnt(2)
	v_add_f32_e32 v0, v0, v74
	v_add_f32_e32 v0, v0, v75
	s_waitcnt lgkmcnt(1)
	v_add_f32_e32 v0, v0, v76
	v_add_f32_e32 v0, v0, v77
	s_waitcnt lgkmcnt(0)
	v_add_f32_e32 v0, v0, v78
	v_add_f32_e32 v2, v0, v79
	v_lshl_add_u64 v[0:1], v[80:81], 2, s[56:57]
	global_store_dword v[0:1], v2, off sc1
	s_branch .LBB0_22
